# barrier: dead TOPGEN/XGEN atomics removed; scan S1: per-row a_cs LDS reads issued up front (no exposed LDS round trip per row group)
# speedup vs baseline: 1.0308x; 1.0023x over previous
; DI u32x4 pack8(const float (&f)[8]) { u32x4 r; r[0] = pk2(f[0], f[1]); r[1] = pk2(f[2], f[3]); r[2] = pk2(f[4], f[5]); r[3] = pk2(f[6], f[7]); return r; }
; DI void ssd_scan_phase(bf16_t* P, const bf16_t* BT, const bf16_t* Cc, const bf16_t* CB, const float* dt, const float* acs,
;                        const float* cw, const float* cb, const float* Dp, char* lds, bool dry, int mode, float* Sbuf) {
;     ...
;       const float* cAcs = sAcs + (c & 1) * 128; const float* cDt = sDt + (c & 1) * 128;
;       {
;         int xl = xl_, xc = xc_, r0 = r0_, cch = cch_;
;         asm volatile("" : "+v"(xl), "+v"(xc), "+v"(r0), "+v"(cch));
;         const f32x4 a0 = *(const f32x4*)(cAcs + cch * 8), a1 = *(const f32x4*)(cAcs + cch * 8 + 4);
;         const float L2E = 1.44269504f;
;         const float as[8] = {a0[0] * L2E, a0[1] * L2E, a0[2] * L2E, a0[3] * L2E, a1[0] * L2E, a1[1] * L2E, a1[2] * L2E, a1[3] * L2E};
; #pragma unroll
;         for (int j = 0; j < 4; ++j) {
;           const int r = r0 + 32 * j;
;           *(u32x4*)(sBT + swz128(r, cch)) = rB[j];
;           if (mode == 0) {
;             *(u32x4*)(sC + swz128(r, cch)) = rC[j];
;             float f[8]; unpack8(rCB[j], f);
;             const float el = cAcs[r] * L2E;
;             const int lim = r - cch * 8;
; #pragma unroll
;             for (int e = 0; e < 8; ++e) f[e] = (e <= lim) ? f[e] * __builtin_amdgcn_exp2f(el - as[e]) : 0.f;
;             *(u32x4*)(sCBL + swz128(r, cch)) = pack8(f);
;           }
;         }
.LBB0_1054:
	s_and_b32 s90, s80, 1
	s_lshl_b32 s78, s90, 9
	s_add_i32 s88, s78, 0
	s_add_i32 s88, s88, 0x22800
	v_mov_b32_e32 v34, v177
	v_mov_b32_e32 v40, v178
	v_mov_b32_e32 v29, v176
	v_mov_b32_e32 v41, v179
	s_mov_b64 s[78:79], -1
	v_lshl_add_u32 v24, v34, 5, s88
	ds_read_b128 v[20:23], v24
	ds_read_b128 v[30:33], v24 offset:16
	v_lshl_add_u32 v47, v29, 2, s88
	ds_read_b32 v48, v47
	ds_read_b32 v49, v47 offset:128
	ds_read_b32 v50, v47 offset:256
	ds_read_b32 v51, v47 offset:384
	v_lshlrev_b32_e32 v26, 3, v34
	s_and_b64 vcc, exec, s[56:57]
	s_waitcnt lgkmcnt(5)
	v_mul_f32_e32 v24, 0x3fb8aa3b, v23
	s_waitcnt lgkmcnt(4)
	v_mul_f32_e32 v23, 0x3fb8aa3b, v30
	v_bitop3_b32 v30, v29, v34, 15 bitop3:0x6c
	v_mul_f32_e32 v27, 0x3fb8aa3b, v21
	v_mul_f32_e32 v21, 0x3fb8aa3b, v32
	v_lshlrev_b32_e32 v30, 4, v30
	v_lshlrev_b32_e32 v32, 8, v29
	v_mul_f32_e32 v25, 0x3fb8aa3b, v22
	v_mul_f32_e32 v22, 0x3fb8aa3b, v31
	v_add_u32_e32 v31, v30, v32
	v_mul_f32_e32 v28, 0x3fb8aa3b, v20
	v_mul_f32_e32 v20, 0x3fb8aa3b, v33
	v_add_u32_e32 v33, 0, v31
	v_add_u32_e32 v31, 0x10000, v33
	s_waitcnt vmcnt(3)
	ds_write_b128 v31, v[60:63]
	v_lshl_add_u32 v31, v29, 2, s88
	s_cbranch_vccnz .LBB0_1056
	ds_write_b128 v33, v[52:55] offset:32768
	v_lshlrev_b32_e32 v34, 16, v56
	v_sub_u32_e32 v46, v29, v26
	v_cmp_lt_i32_e32 vcc, -1, v46
	v_lshlrev_b32_e32 v42, 16, v58
	s_waitcnt lgkmcnt(0)
	v_fma_f32 v35, v48, s29, -v28
	v_fma_f32 v37, v48, s29, -v27
	v_exp_f32_e32 v36, v35
	v_exp_f32_e32 v37, v37
	v_fma_f32 v38, v48, s29, -v25
	v_fma_f32 v39, v48, s29, -v24
	v_exp_f32_e32 v38, v38
	v_exp_f32_e32 v39, v39
	v_and_b32_e32 v35, 0xffff0000, v56
	v_pk_mul_f32 v[34:35], v[36:37], v[34:35]
	v_lshlrev_b32_e32 v36, 16, v57
	v_and_b32_e32 v37, 0xffff0000, v57
	v_pk_mul_f32 v[36:37], v[38:39], v[36:37]
	v_fma_f32 v38, v48, s29, -v23
	v_fma_f32 v39, v48, s29, -v22
	v_cvt_pk_bf16_f32 v34, v34, v35
	v_exp_f32_e32 v38, v38
	v_exp_f32_e32 v39, v39
	v_cndmask_b32_e32 v35, 0, v34, vcc
	v_lshrrev_b32_e32 v34, 16, v34
	v_cmp_lt_i32_e32 vcc, 0, v46
	v_fma_f32 v44, v48, s29, -v21
	v_fma_f32 v45, v48, s29, -v20
	v_cndmask_b32_e32 v34, 0, v34, vcc
	v_perm_b32 v34, v34, v35, s97
	v_cvt_pk_bf16_f32 v35, v36, v37
	v_cmp_lt_i32_e32 vcc, 1, v46
	v_and_b32_e32 v43, 0xffff0000, v58
	v_exp_f32_e32 v44, v44
	v_exp_f32_e32 v45, v45
	v_cndmask_b32_e32 v36, 0, v35, vcc
	v_lshrrev_b32_e32 v35, 16, v35
	v_cmp_lt_i32_e32 vcc, 2, v46
	v_pk_mul_f32 v[38:39], v[38:39], v[42:43]
	v_lshlrev_b32_e32 v42, 16, v59
	v_cndmask_b32_e32 v35, 0, v35, vcc
	v_perm_b32 v35, v35, v36, s97
	v_cvt_pk_bf16_f32 v36, v38, v39
	v_cmp_lt_i32_e32 vcc, 3, v46
	v_and_b32_e32 v43, 0xffff0000, v59
	v_pk_mul_f32 v[42:43], v[44:45], v[42:43]
	v_cndmask_b32_e32 v37, 0, v36, vcc
	v_lshrrev_b32_e32 v36, 16, v36
	v_cmp_lt_i32_e32 vcc, 4, v46
	s_mov_b64 s[78:79], 0
	s_nop 0
	v_cndmask_b32_e32 v36, 0, v36, vcc
	v_perm_b32 v36, v36, v37, s97
	v_cvt_pk_bf16_f32 v37, v42, v43
	v_cmp_lt_i32_e32 vcc, 5, v46
	s_waitcnt vmcnt(2)
	v_lshlrev_b32_e32 v42, 16, v70
	v_and_b32_e32 v43, 0xffff0000, v70
	v_cndmask_b32_e32 v38, 0, v37, vcc
	v_lshrrev_b32_e32 v37, 16, v37
	v_cmp_lt_i32_e32 vcc, 6, v46
	s_nop 1
	v_cndmask_b32_e32 v37, 0, v37, vcc
	v_perm_b32 v37, v37, v38, s97
	ds_write_b128 v33, v[34:37]
	v_add_u32_e32 v33, 32, v29
	v_lshlrev_b32_e32 v34, 8, v33
	v_add3_u32 v46, v30, v34, 0
	v_add_u32_e32 v34, 0x10000, v46
	ds_write_b128 v34, v[76:79]
	ds_write_b128 v46, v[64:67] offset:32768
	v_lshlrev_b32_e32 v36, 16, v68
	v_and_b32_e32 v37, 0xffff0000, v68
	v_sub_u32_e32 v33, v33, v26
	v_cmp_lt_i32_e32 vcc, -1, v33
	v_fma_f32 v34, v49, s29, -v28
	v_fma_f32 v35, v49, s29, -v27
	v_exp_f32_e32 v34, v34
	v_exp_f32_e32 v35, v35
	v_fma_f32 v38, v49, s29, -v25
	v_fma_f32 v39, v49, s29, -v24
	v_exp_f32_e32 v38, v38
	v_exp_f32_e32 v39, v39
	v_pk_mul_f32 v[34:35], v[34:35], v[36:37]
	v_lshlrev_b32_e32 v36, 16, v69
	v_and_b32_e32 v37, 0xffff0000, v69
	v_pk_mul_f32 v[36:37], v[38:39], v[36:37]
	v_fma_f32 v38, v49, s29, -v23
	v_fma_f32 v39, v49, s29, -v22
	v_cvt_pk_bf16_f32 v34, v34, v35
	v_exp_f32_e32 v38, v38
	v_exp_f32_e32 v39, v39
	v_cndmask_b32_e32 v35, 0, v34, vcc
	v_cmp_lt_i32_e32 vcc, 0, v33
	v_fma_f32 v44, v49, s29, -v21
	v_fma_f32 v45, v49, s29, -v20
	v_cndmask_b32_sdwa v34, v1, v34, vcc dst_sel:DWORD dst_unused:UNUSED_PAD src0_sel:DWORD src1_sel:WORD_1
	v_perm_b32 v34, v34, v35, s97
	v_cvt_pk_bf16_f32 v35, v36, v37
	v_cmp_lt_i32_e32 vcc, 1, v33
	v_exp_f32_e32 v44, v44
	v_exp_f32_e32 v45, v45
	v_cndmask_b32_e32 v36, 0, v35, vcc
	v_cmp_lt_i32_e32 vcc, 2, v33
	v_pk_mul_f32 v[38:39], v[38:39], v[42:43]
	v_lshlrev_b32_e32 v42, 16, v71
	v_cndmask_b32_sdwa v35, v1, v35, vcc dst_sel:DWORD dst_unused:UNUSED_PAD src0_sel:DWORD src1_sel:WORD_1
	v_perm_b32 v35, v35, v36, s97
	v_cvt_pk_bf16_f32 v36, v38, v39
	v_cmp_lt_i32_e32 vcc, 3, v33
	v_and_b32_e32 v43, 0xffff0000, v71
	v_pk_mul_f32 v[42:43], v[44:45], v[42:43]
	v_cndmask_b32_e32 v37, 0, v36, vcc
	v_cmp_lt_i32_e32 vcc, 4, v33
	s_nop 1
	v_cndmask_b32_sdwa v36, v1, v36, vcc dst_sel:DWORD dst_unused:UNUSED_PAD src0_sel:DWORD src1_sel:WORD_1
	v_perm_b32 v36, v36, v37, s97
	v_cvt_pk_bf16_f32 v37, v42, v43
	v_cmp_lt_i32_e32 vcc, 5, v33
	s_nop 1
	v_cndmask_b32_e32 v38, 0, v37, vcc
	v_cmp_lt_i32_e32 vcc, 6, v33
	s_nop 1
	v_cndmask_b32_sdwa v33, v1, v37, vcc dst_sel:DWORD dst_unused:UNUSED_PAD src0_sel:DWORD src1_sel:WORD_1
	v_perm_b32 v37, v33, v38, s97
	ds_write_b128 v46, v[34:37]

; DI u32x4 pack8(const float (&f)[8]) { u32x4 r; r[0] = pk2(f[0], f[1]); r[1] = pk2(f[2], f[3]); r[2] = pk2(f[4], f[5]); r[3] = pk2(f[6], f[7]); return r; }
; DI void ssd_scan_phase(bf16_t* P, const bf16_t* BT, const bf16_t* Cc, const bf16_t* CB, const float* dt, const float* acs,
;                        const float* cw, const float* cb, const float* Dp, char* lds, bool dry, int mode, float* Sbuf) {
;     ...
;         for (int j = 0; j < 4; ++j) {
;           const int r = r0 + 32 * j;
;           *(u32x4*)(sBT + swz128(r, cch)) = rB[j];
;           if (mode == 0) {
;             *(u32x4*)(sC + swz128(r, cch)) = rC[j];
;             float f[8]; unpack8(rCB[j], f);
;             const float el = cAcs[r] * L2E;
;             const int lim = r - cch * 8;
; #pragma unroll
;             for (int e = 0; e < 8; ++e) f[e] = (e <= lim) ? f[e] * __builtin_amdgcn_exp2f(el - as[e]) : 0.f;
;             *(u32x4*)(sCBL + swz128(r, cch)) = pack8(f);
;           }
;         }
.LBB0_1061:
	ds_write_b128 v33, v[72:75] offset:32768
	v_sub_u32_e32 v46, v34, v26
	v_lshlrev_b32_e32 v34, 16, v80
	v_cmp_lt_i32_e32 vcc, -1, v46
	v_lshlrev_b32_e32 v42, 16, v82
	v_fma_f32 v35, v50, s29, -v28
	v_fma_f32 v37, v50, s29, -v27
	v_exp_f32_e32 v36, v35
	v_exp_f32_e32 v37, v37
	v_fma_f32 v38, v50, s29, -v25
	v_fma_f32 v39, v50, s29, -v24
	v_exp_f32_e32 v38, v38
	v_exp_f32_e32 v39, v39
	v_and_b32_e32 v35, 0xffff0000, v80
	v_pk_mul_f32 v[34:35], v[36:37], v[34:35]
	v_lshlrev_b32_e32 v36, 16, v81
	v_and_b32_e32 v37, 0xffff0000, v81
	v_pk_mul_f32 v[36:37], v[38:39], v[36:37]
	v_fma_f32 v38, v50, s29, -v23
	v_fma_f32 v39, v50, s29, -v22
	v_cvt_pk_bf16_f32 v34, v34, v35
	v_exp_f32_e32 v38, v38
	v_exp_f32_e32 v39, v39
	v_cndmask_b32_e32 v35, 0, v34, vcc
	v_lshrrev_b32_e32 v34, 16, v34
	v_cmp_lt_i32_e32 vcc, 0, v46
	v_fma_f32 v44, v50, s29, -v21
	v_fma_f32 v45, v50, s29, -v20
	v_cndmask_b32_e32 v34, 0, v34, vcc
	v_perm_b32 v34, v34, v35, s97
	v_cvt_pk_bf16_f32 v35, v36, v37
	v_cmp_lt_i32_e32 vcc, 1, v46
	v_and_b32_e32 v43, 0xffff0000, v82
	v_exp_f32_e32 v44, v44
	v_exp_f32_e32 v45, v45
	v_cndmask_b32_e32 v36, 0, v35, vcc
	v_lshrrev_b32_e32 v35, 16, v35
	v_cmp_lt_i32_e32 vcc, 2, v46
	v_pk_mul_f32 v[38:39], v[38:39], v[42:43]
	v_lshlrev_b32_e32 v42, 16, v83
	v_cndmask_b32_e32 v35, 0, v35, vcc
	v_perm_b32 v35, v35, v36, s97
	v_cvt_pk_bf16_f32 v36, v38, v39
	v_cmp_lt_i32_e32 vcc, 3, v46
	v_and_b32_e32 v43, 0xffff0000, v83
	v_pk_mul_f32 v[42:43], v[44:45], v[42:43]
	v_cndmask_b32_e32 v37, 0, v36, vcc
	v_lshrrev_b32_e32 v36, 16, v36
	v_cmp_lt_i32_e32 vcc, 4, v46
	v_add_u32_e32 v29, 0x60, v29
	s_nop 0
	v_cndmask_b32_e32 v36, 0, v36, vcc
	v_perm_b32 v36, v36, v37, s97
	v_cvt_pk_bf16_f32 v37, v42, v43
	v_cmp_lt_i32_e32 vcc, 5, v46
	s_nop 1
	v_cndmask_b32_e32 v38, 0, v37, vcc
	v_lshrrev_b32_e32 v37, 16, v37
	v_cmp_lt_i32_e32 vcc, 6, v46
	s_nop 1
	v_cndmask_b32_e32 v37, 0, v37, vcc
	v_perm_b32 v37, v37, v38, s97
	ds_write_b128 v33, v[34:37]
	v_lshlrev_b32_e32 v33, 8, v29
	v_add3_u32 v33, v30, v33, 0
	v_add_u32_e32 v30, 0x10000, v33
	s_waitcnt vmcnt(0)
	ds_write_b128 v30, v[104:107]
	ds_write_b128 v33, v[84:87] offset:32768
	v_sub_u32_e32 v35, v29, v26
	v_and_b32_e32 v29, 0xffff0000, v88
	v_cmp_lt_i32_e32 vcc, -1, v35
	v_fma_f32 v26, v51, s29, -v28
	v_fma_f32 v27, v51, s29, -v27
	v_exp_f32_e32 v26, v26
	v_exp_f32_e32 v27, v27
	v_fma_f32 v25, v51, s29, -v25
	v_fma_f32 v24, v51, s29, -v24
	v_exp_f32_e32 v30, v25
	v_exp_f32_e32 v31, v24
	v_lshlrev_b32_e32 v28, 16, v88
	v_pk_mul_f32 v[24:25], v[26:27], v[28:29]
	v_lshlrev_b32_e32 v26, 16, v89
	v_and_b32_e32 v27, 0xffff0000, v89
	v_fma_f32 v23, v51, s29, -v23
	v_fma_f32 v22, v51, s29, -v22
	v_fma_f32 v21, v51, s29, -v21
	v_fma_f32 v20, v51, s29, -v20
	v_pk_mul_f32 v[26:27], v[30:31], v[26:27]
	v_exp_f32_e32 v28, v23
	v_exp_f32_e32 v29, v22
	v_exp_f32_e32 v30, v21
	v_exp_f32_e32 v31, v20
	v_lshlrev_b32_e32 v22, 16, v90
	v_and_b32_e32 v23, 0xffff0000, v90
	v_lshlrev_b32_e32 v20, 16, v91
	v_and_b32_e32 v21, 0xffff0000, v91
	v_pk_mul_f32 v[22:23], v[28:29], v[22:23]
	v_pk_mul_f32 v[28:29], v[30:31], v[20:21]
	v_cvt_pk_bf16_f32 v20, v24, v25
	v_cndmask_b32_e32 v21, 0, v20, vcc
	v_cmp_lt_i32_e32 vcc, 0, v35
	v_cvt_pk_bf16_f32 v22, v22, v23
	s_nop 0
	v_cndmask_b32_sdwa v20, v1, v20, vcc dst_sel:DWORD dst_unused:UNUSED_PAD src0_sel:DWORD src1_sel:WORD_1
	v_perm_b32 v20, v20, v21, s97
	v_cvt_pk_bf16_f32 v21, v26, v27
	v_cmp_lt_i32_e32 vcc, 1, v35
	s_nop 1
	v_cndmask_b32_e32 v24, 0, v21, vcc
	v_cmp_lt_i32_e32 vcc, 2, v35
	s_nop 1
	v_cndmask_b32_sdwa v21, v1, v21, vcc dst_sel:DWORD dst_unused:UNUSED_PAD src0_sel:DWORD src1_sel:WORD_1
	v_cmp_lt_i32_e32 vcc, 3, v35
	v_perm_b32 v21, v21, v24, s97
	s_nop 0
	v_cndmask_b32_e32 v23, 0, v22, vcc
	v_cmp_lt_i32_e32 vcc, 4, v35
	s_nop 1
	v_cndmask_b32_sdwa v22, v1, v22, vcc dst_sel:DWORD dst_unused:UNUSED_PAD src0_sel:DWORD src1_sel:WORD_1
	v_perm_b32 v22, v22, v23, s97
	v_cvt_pk_bf16_f32 v23, v28, v29
	v_cmp_lt_i32_e32 vcc, 5, v35
	s_nop 1
	v_cndmask_b32_e32 v24, 0, v23, vcc
	v_cmp_lt_i32_e32 vcc, 6, v35
	s_nop 1
	v_cndmask_b32_sdwa v23, v1, v23, vcc dst_sel:DWORD dst_unused:UNUSED_PAD src0_sel:DWORD src1_sel:WORD_1
	v_perm_b32 v23, v23, v24, s97
	ds_write_b128 v33, v[20:23]
	s_cbranch_execnz .LBB0_1060

; DI unsigned xb_ld(unsigned* p)              { return __hip_atomic_load(p, __ATOMIC_RELAXED, __HIP_MEMORY_SCOPE_AGENT); }
; DI unsigned xb_add(unsigned* p, unsigned v) { return __hip_atomic_fetch_add(p, v, __ATOMIC_RELAXED, __HIP_MEMORY_SCOPE_AGENT); }
; #define XB_SPIN(cond, bar) do { unsigned _sp = 0; while (cond) { __builtin_amdgcn_s_sleep(1); \
;     if ((++_sp & 255u) == 0u) { if (xb_ld(&(bar)[XB_TMO])) break; if (_sp > XB_SPIN_CAP) { atomicAdd(&(bar)[XB_TMO], 1u); break; } } } } while (0)
; DI void xcd_barrier(const XcdBarrier& b) {
;     ...
;       const unsigned og = xb_add(&bar[XB_TOP], 1u);
;       const unsigned tg = og / nx;
;       if (og + 1u == (tg + 1u) * nx) xb_add(&bar[XB_TOPGEN], 1u);
;       else XB_SPIN(xb_ld(&bar[XB_TOPGEN]) == tg, bar);
.LBB0_2097:
	s_or_b64 exec, exec, s[40:41]
	s_waitcnt vmcnt(0)
	v_readfirstlane_b32 s28, v3
	v_sub_u32_e32 v4, 0, v2
	v_readlane_b32 s4, v254, 62
	v_add_u32_e32 v3, s28, v0
	v_cvt_f32_u32_e32 v0, v2
	v_readlane_b32 s5, v254, 63
	s_mov_b64 s[40:41], 0
	v_rcp_iflag_f32_e32 v0, v0
	s_nop 0
	v_mul_f32_e32 v0, 0x4f7ffffe, v0
	v_cvt_u32_f32_e32 v0, v0
	v_mul_lo_u32 v4, v4, v0
	v_mul_hi_u32 v4, v0, v4
	v_add_u32_e32 v0, v0, v4
	v_mul_hi_u32 v0, v3, v0
	v_mul_lo_u32 v4, v0, v2
	v_sub_u32_e32 v4, v3, v4
	v_cmp_ge_u32_e32 vcc, v4, v2
	v_add_u32_e32 v5, 1, v0
	v_add_u32_e32 v3, 1, v3
	v_cndmask_b32_e32 v0, v0, v5, vcc
	v_sub_u32_e32 v5, v4, v2
	v_cndmask_b32_e32 v4, v4, v5, vcc
	v_cmp_ge_u32_e32 vcc, v4, v2
	v_add_u32_e32 v4, 1, v0
	s_nop 0
	v_cndmask_b32_e32 v0, v0, v4, vcc
	v_mul_lo_u32 v4, v2, v0
	v_add_u32_e32 v2, v4, v2
	v_mov_b32_e32 v7, v2
	v_cmp_ne_u32_e32 vcc, v3, v2
	v_mov_b64_e32 v[2:3], s[4:5]
	s_and_saveexec_b64 s[30:31], vcc
	s_cbranch_execz .LBB0_2109
	v_readlane_b32 s4, v254, 60
	v_readlane_b32 s5, v254, 61
	s_mov_b64 s[42:43], 0
	s_nop 3
	global_load_dword v2, v1, s[4:5] sc1
	s_waitcnt vmcnt(0)
	v_cmp_lt_u32_e32 vcc, v2, v7
	s_and_saveexec_b64 s[40:41], vcc
	s_cbranch_execz .LBB0_2108
	s_mov_b32 s28, 1
	s_branch .LBB0_2101

; DI unsigned xb_add(unsigned* p, unsigned v) { return __hip_atomic_fetch_add(p, v, __ATOMIC_RELAXED, __HIP_MEMORY_SCOPE_AGENT); }
; DI void xcd_barrier(const XcdBarrier& b) {
;     ...
;       xb_add(&bar[XB_XGEN(b.x)], 1u);
.LBB0_2112:
	s_bcnt1_i32_b64 s28, s[30:31]
	v_readlane_b32 s4, v254, 58
	v_mov_b32_e32 v0, s28
	v_readlane_b32 s5, v254, 59
	s_nop 4
	s_getpc_b64 s[98:99]
